# grid barrier: non-leader workgroups issue their acquire invalidate before polling the generation word instead of after
# speedup vs baseline: 1.0119x; 1.0067x over previous
.LBB0_85:
	s_or_b64 exec, exec, s[10:11]
	v_cvt_f32_u32_e32 v4, v2
	s_waitcnt vmcnt(0)
	v_readfirstlane_b32 s0, v3
	v_sub_u32_e32 v3, 0, v2
	v_rcp_iflag_f32_e32 v4, v4
	v_add_u32_e32 v5, s0, v1
	v_mul_f32_e32 v4, 0x4f7ffffe, v4
	v_cvt_u32_f32_e32 v4, v4
	v_mul_lo_u32 v1, v3, v4
	v_mul_hi_u32 v1, v4, v1
	v_add_u32_e32 v1, v4, v1
	v_mul_hi_u32 v1, v5, v1
	v_mul_lo_u32 v3, v1, v2
	v_sub_u32_e32 v3, v5, v3
	v_add_u32_e32 v4, 1, v1
	v_cmp_ge_u32_e32 vcc, v3, v2
	s_nop 1
	v_cndmask_b32_e32 v1, v1, v4, vcc
	v_sub_u32_e32 v4, v3, v2
	v_cndmask_b32_e32 v3, v3, v4, vcc
	v_add_u32_e32 v4, 1, v1
	v_cmp_ge_u32_e32 vcc, v3, v2
	v_add_u32_e32 v3, 1, v5
	s_nop 0
	v_cndmask_b32_e32 v1, v1, v4, vcc
	v_mul_lo_u32 v4, v2, v1
	v_add_u32_e32 v2, v4, v2
	v_cmp_ne_u32_e32 vcc, v3, v2
	s_and_saveexec_b64 s[0:1], vcc
	s_xor_b64 s[8:9], exec, s[0:1]
	s_cbranch_execz .LBB0_99
	buffer_inv sc1
	s_waitcnt lgkmcnt(0)
	v_mov_b32_e32 v0, 0x2000
	global_load_dword v0, v0, s[6:7] offset:1024 sc1
	s_add_u32 s14, s6, 0x2400
	s_addc_u32 s15, s7, 0
	s_waitcnt vmcnt(0)
	v_cmp_eq_u32_e32 vcc, v0, v1
	s_and_saveexec_b64 s[10:11], vcc
	s_cbranch_execz .LBB0_98
	v_readlane_b32 s0, v251, 9
	v_readlane_b32 s1, v251, 10
	s_add_u32 s12, s0, 0xde70200
	s_addc_u32 s13, s1, 0
	s_mov_b32 s0, 1
	s_mov_b64 s[16:17], 0
	v_mov_b32_e32 v0, 0
	s_branch .LBB0_89

.LBB0_98:
	s_or_b64 exec, exec, s[10:11]
	s_waitcnt vmcnt(0)
	s_waitcnt vmcnt(0)

.LBB0_760:
	s_or_b64 exec, exec, s[12:13]
	v_cvt_f32_u32_e32 v4, v2
	v_readlane_b32 s0, v251, 5
	s_lshl_b32 s6, s0, 6
	s_waitcnt vmcnt(0)
	v_readfirstlane_b32 s0, v3
	v_rcp_iflag_f32_e32 v4, v4
	v_sub_u32_e32 v3, 0, v2
	v_add_u32_e32 v5, s0, v1
	v_mul_f32_e32 v4, 0x4f7ffffe, v4
	v_cvt_u32_f32_e32 v4, v4
	v_mul_lo_u32 v1, v3, v4
	v_mul_hi_u32 v1, v4, v1
	v_add_u32_e32 v1, v4, v1
	v_mul_hi_u32 v1, v5, v1
	v_mul_lo_u32 v3, v1, v2
	v_sub_u32_e32 v3, v5, v3
	v_add_u32_e32 v4, 1, v1
	v_cmp_ge_u32_e32 vcc, v3, v2
	s_nop 1
	v_cndmask_b32_e32 v1, v1, v4, vcc
	v_sub_u32_e32 v4, v3, v2
	v_cndmask_b32_e32 v3, v3, v4, vcc
	v_add_u32_e32 v4, 1, v1
	v_cmp_ge_u32_e32 vcc, v3, v2
	v_add_u32_e32 v3, 1, v5
	s_nop 0
	v_cndmask_b32_e32 v1, v1, v4, vcc
	v_mul_lo_u32 v4, v2, v1
	v_add_u32_e32 v2, v4, v2
	v_cmp_ne_u32_e32 vcc, v3, v2
	s_and_saveexec_b64 s[0:1], vcc
	s_xor_b64 s[10:11], exec, s[0:1]
	s_cbranch_execz .LBB0_774
	buffer_inv sc1
	s_waitcnt lgkmcnt(0)
	v_mov_b32_e32 v0, 0x2000
	global_load_dword v0, v0, s[8:9] offset:1024 sc1
	s_add_u32 s16, s8, 0x2400
	s_addc_u32 s17, s9, 0
	s_waitcnt vmcnt(0)
	v_cmp_eq_u32_e32 vcc, v0, v1
	s_and_saveexec_b64 s[12:13], vcc
	s_cbranch_execz .LBB0_773
	v_readlane_b32 s0, v251, 9
	v_readlane_b32 s1, v251, 10
	s_add_u32 s14, s0, 0xde70200
	s_addc_u32 s15, s1, 0
	s_mov_b32 s0, 1
	s_mov_b64 s[18:19], 0
	v_mov_b32_e32 v0, 0
	s_branch .LBB0_764

.LBB0_773:
	s_or_b64 exec, exec, s[12:13]
	s_waitcnt vmcnt(0)
	s_waitcnt vmcnt(0)

.LBB0_826:
	global_atomic_add v4, v[162:163], v200, off sc0
	v_cvt_f32_u32_e32 v0, v3
	v_sub_u32_e32 v5, 0, v3
	v_rcp_iflag_f32_e32 v0, v0
	s_nop 0
	v_mul_f32_e32 v0, 0x4f7ffffe, v0
	v_cvt_u32_f32_e32 v0, v0
	v_mul_lo_u32 v5, v5, v0
	v_mul_hi_u32 v5, v0, v5
	v_add_u32_e32 v0, v0, v5
	s_waitcnt vmcnt(0)
	v_mul_hi_u32 v0, v4, v0
	v_mul_lo_u32 v5, v0, v3
	v_sub_u32_e32 v5, v4, v5
	v_add_u32_e32 v6, 1, v0
	v_cmp_ge_u32_e32 vcc, v5, v3
	v_add_u32_e32 v4, 1, v4
	s_nop 0
	v_cndmask_b32_e32 v0, v0, v6, vcc
	v_sub_u32_e32 v6, v5, v3
	v_cndmask_b32_e32 v5, v5, v6, vcc
	v_add_u32_e32 v6, 1, v0
	v_cmp_ge_u32_e32 vcc, v5, v3
	s_nop 1
	v_cndmask_b32_e32 v0, v0, v6, vcc
	v_mul_lo_u32 v5, v3, v0
	v_add_u32_e32 v3, v5, v3
	v_cmp_ne_u32_e32 vcc, v4, v3
	s_and_saveexec_b64 s[0:1], vcc
	s_xor_b64 s[10:11], exec, s[0:1]
	s_cbranch_execz .LBB0_840
	buffer_inv sc1
	s_waitcnt lgkmcnt(0)
	global_load_dword v2, v[164:165], off sc1
	s_waitcnt vmcnt(0)
	v_cmp_eq_u32_e32 vcc, v2, v0
	s_and_saveexec_b64 s[12:13], vcc
	s_cbranch_execz .LBB0_839
	s_mov_b32 s0, 1
	s_mov_b64 s[14:15], 0
	s_branch .LBB0_830

.LBB0_1048:
	global_atomic_add v4, v[162:163], v200, off sc0
	v_cvt_f32_u32_e32 v0, v3
	v_sub_u32_e32 v5, 0, v3
	v_rcp_iflag_f32_e32 v0, v0
	s_nop 0
	v_mul_f32_e32 v0, 0x4f7ffffe, v0
	v_cvt_u32_f32_e32 v0, v0
	v_mul_lo_u32 v5, v5, v0
	v_mul_hi_u32 v5, v0, v5
	v_add_u32_e32 v0, v0, v5
	s_waitcnt vmcnt(0)
	v_mul_hi_u32 v0, v4, v0
	v_mul_lo_u32 v5, v0, v3
	v_sub_u32_e32 v5, v4, v5
	v_add_u32_e32 v6, 1, v0
	v_cmp_ge_u32_e32 vcc, v5, v3
	v_add_u32_e32 v4, 1, v4
	s_nop 0
	v_cndmask_b32_e32 v0, v0, v6, vcc
	v_sub_u32_e32 v6, v5, v3
	v_cndmask_b32_e32 v5, v5, v6, vcc
	v_add_u32_e32 v6, 1, v0
	v_cmp_ge_u32_e32 vcc, v5, v3
	s_nop 1
	v_cndmask_b32_e32 v0, v0, v6, vcc
	v_mul_lo_u32 v5, v3, v0
	v_add_u32_e32 v3, v5, v3
	v_cmp_ne_u32_e32 vcc, v4, v3
	s_and_saveexec_b64 s[0:1], vcc
	s_xor_b64 s[8:9], exec, s[0:1]
	s_cbranch_execz .LBB0_1062
	buffer_inv sc1
	s_waitcnt lgkmcnt(0)
	global_load_dword v2, v[164:165], off sc1
	s_waitcnt vmcnt(0)
	v_cmp_eq_u32_e32 vcc, v2, v0
	s_and_saveexec_b64 s[10:11], vcc
	s_cbranch_execz .LBB0_1061
	s_mov_b32 s0, 1
	s_mov_b64 s[12:13], 0
	s_branch .LBB0_1052
